# grid barrier: the last leader bumps every XCD generation word directly; XCD leaders no longer relay the release
# baseline (speedup 1.0000x reference)
.LBB0_846:
	s_or_b64 exec, exec, s[4:5]
	s_and_saveexec_b64 s[4:5], s[8:9]
	s_cbranch_execz .LBB0_848
	global_atomic_add v[0:1], v201, off
	v_readlane_b32 s14, v246, 37
	v_readlane_b32 s15, v246, 38
	s_nop 4
	global_atomic_add v200, v201, s[14:15] offset:1024
	global_atomic_add v200, v201, s[14:15] offset:1280
	global_atomic_add v200, v201, s[14:15] offset:1536
	global_atomic_add v200, v201, s[14:15] offset:1792
	global_atomic_add v200, v201, s[14:15] offset:2048
	global_atomic_add v200, v201, s[14:15] offset:2304
	global_atomic_add v200, v201, s[14:15] offset:2560
	global_atomic_add v200, v201, s[14:15] offset:2816
	s_add_u32 s14, s14, 0x800
	s_addc_u32 s15, s15, 0
	global_atomic_add v200, v201, s[14:15] offset:1024
	global_atomic_add v200, v201, s[14:15] offset:1280
	global_atomic_add v200, v201, s[14:15] offset:1536
	global_atomic_add v200, v201, s[14:15] offset:1792
	global_atomic_add v200, v201, s[14:15] offset:2048
	global_atomic_add v200, v201, s[14:15] offset:2304
	global_atomic_add v200, v201, s[14:15] offset:2560
	global_atomic_add v200, v201, s[14:15] offset:2816
.LBB0_848:
	s_or_b64 exec, exec, s[4:5]
	s_mov_b64 s[4:5], exec
	v_mbcnt_lo_u32_b32 v0, s4, 0
	v_mbcnt_hi_u32_b32 v0, s5, v0
	v_cmp_eq_u32_e32 vcc, 0, v0
	s_waitcnt vmcnt(0)
	s_and_saveexec_b64 s[8:9], vcc
	s_cbranch_execz .LBB0_850
	s_bcnt1_i32_b64 s4, s[4:5]
	v_mov_b32_e32 v0, s4
.LBB0_850:
	s_or_b64 exec, exec, s[8:9]
	s_waitcnt vmcnt(0)
